# rebalanced deferred convert: layer-3 mlp_w1 fully + three quarters of layer-3 mlp_w2 deferred to K/V-GEMM-idle workgroups (9.3 items per wave), last quarter stays up front
# baseline (speedup 1.0000x reference)
.Lmy_cvw2_done:
	s_add_u32 s64, s64, 0x3000000
	s_addc_u32 s65, s65, 0
	s_add_u32 s66, s66, 0x3000
	s_addc_u32 s67, s67, 0
	s_mov_b32 s78, 1
	s_mov_b32 s70, 0
	s_mov_b64 s[72:73], s[64:65]
	global_load_dword v100, v180, s[72:73]
	s_add_u32 s72, s72, 0x4000
	s_addc_u32 s73, s73, 0
	global_load_dword v101, v180, s[72:73]
	s_add_u32 s72, s72, 0x4000
	s_addc_u32 s73, s73, 0
	global_load_dword v102, v180, s[72:73]
	s_add_u32 s72, s72, 0x4000
	s_addc_u32 s73, s73, 0
	global_load_dword v103, v180, s[72:73]
	s_add_u32 s72, s72, 0x4000
	s_addc_u32 s73, s73, 0
	global_load_dword v104, v180, s[72:73]
	s_add_u32 s72, s72, 0x4000
	s_addc_u32 s73, s73, 0
	global_load_dword v105, v180, s[72:73]
	s_add_u32 s72, s72, 0x4000
	s_addc_u32 s73, s73, 0
	global_load_dword v106, v180, s[72:73]
	s_add_u32 s72, s72, 0x4000
	s_addc_u32 s73, s73, 0
	global_load_dword v107, v180, s[72:73]
	s_add_u32 s72, s72, 0x4000
	s_addc_u32 s73, s73, 0
	global_load_dword v108, v180, s[72:73]
	s_add_u32 s72, s72, 0x4000
	s_addc_u32 s73, s73, 0
	global_load_dword v109, v180, s[72:73]
	s_add_u32 s72, s72, 0x4000
	s_addc_u32 s73, s73, 0
	global_load_dword v110, v180, s[72:73]
	s_add_u32 s72, s72, 0x4000
	s_addc_u32 s73, s73, 0
	global_load_dword v111, v180, s[72:73]
	s_add_u32 s72, s72, 0x4000
	s_addc_u32 s73, s73, 0
	global_load_dword v112, v180, s[72:73]
	s_add_u32 s72, s72, 0x4000
	s_addc_u32 s73, s73, 0
	global_load_dword v113, v180, s[72:73]
	s_add_u32 s72, s72, 0x4000
	s_addc_u32 s73, s73, 0
	global_load_dword v114, v180, s[72:73]
	s_add_u32 s72, s72, 0x4000
	s_addc_u32 s73, s73, 0
	global_load_dword v115, v180, s[72:73]
	s_add_u32 s72, s72, 0x4000
	s_addc_u32 s73, s73, 0
	global_load_dword v116, v180, s[72:73]
	s_add_u32 s72, s72, 0x4000
	s_addc_u32 s73, s73, 0
	global_load_dword v117, v180, s[72:73]
	s_add_u32 s72, s72, 0x4000
	s_addc_u32 s73, s73, 0
	global_load_dword v118, v180, s[72:73]
	s_add_u32 s72, s72, 0x4000
	s_addc_u32 s73, s73, 0
	global_load_dword v119, v180, s[72:73]
	s_add_u32 s72, s72, 0x4000
	s_addc_u32 s73, s73, 0
	global_load_dword v120, v180, s[72:73]
	s_add_u32 s72, s72, 0x4000
	s_addc_u32 s73, s73, 0
	global_load_dword v121, v180, s[72:73]
	s_add_u32 s72, s72, 0x4000
	s_addc_u32 s73, s73, 0
	global_load_dword v122, v180, s[72:73]
	s_add_u32 s72, s72, 0x4000
	s_addc_u32 s73, s73, 0
	global_load_dword v123, v180, s[72:73]
	s_add_u32 s72, s72, 0x4000
	s_addc_u32 s73, s73, 0
	global_load_dword v124, v180, s[72:73]
	s_add_u32 s72, s72, 0x4000
	s_addc_u32 s73, s73, 0
	global_load_dword v125, v180, s[72:73]
	s_add_u32 s72, s72, 0x4000
	s_addc_u32 s73, s73, 0
	global_load_dword v126, v180, s[72:73]
	s_add_u32 s72, s72, 0x4000
	s_addc_u32 s73, s73, 0
	global_load_dword v127, v180, s[72:73]
	s_add_u32 s72, s72, 0x4000
	s_addc_u32 s73, s73, 0
	global_load_dword v128, v180, s[72:73]
	s_add_u32 s72, s72, 0x4000
	s_addc_u32 s73, s73, 0
	global_load_dword v129, v180, s[72:73]
	s_add_u32 s72, s72, 0x4000
	s_addc_u32 s73, s73, 0
	global_load_dword v130, v180, s[72:73]
	s_add_u32 s72, s72, 0x4000
	s_addc_u32 s73, s73, 0
	global_load_dword v131, v180, s[72:73]
	s_add_u32 s64, s64, 0x1000000
	s_addc_u32 s65, s65, 0

.Lmy_dfw1_done:
	v_lshlrev_b32_e32 v148, 13, v1
	v_or_b32_e32 v148, v148, v16
	v_or_b32_e32 v149, 0, v25
	v_lshlrev_b32_e32 v149, 14, v149
	v_or_b32_e32 v149, v149, v18
	v_or_b32_e32 v150, 8, v25
	v_lshlrev_b32_e32 v150, 14, v150
	v_or_b32_e32 v150, v150, v18
	v_or_b32_e32 v151, 16, v25
	v_lshlrev_b32_e32 v151, 14, v151
	v_or_b32_e32 v151, v151, v18
	v_or_b32_e32 v152, 24, v25
	v_lshlrev_b32_e32 v152, 14, v152
	v_or_b32_e32 v152, v152, v18
	v_readlane_b32 s12, v253, 33
	v_readlane_b32 s13, v253, 34
	s_lshr_b32 s29, s24, 6
	s_and_b32 s30, s24, 63
	s_add_u32 s12, s12, 0xc000000
	s_addc_u32 s13, s13, 0
	s_lshl_b32 s31, s29, 19
	s_add_u32 s12, s12, s31
	s_addc_u32 s13, s13, 0
	s_lshl_b32 s31, s30, 7
	s_add_u32 s12, s12, s31
	s_addc_u32 s13, s13, 0
	s_add_u32 s14, s94, 0xf000000
	s_addc_u32 s15, s95, 0
	s_lshl_b32 s31, s30, 19
	s_add_u32 s14, s14, s31
	s_addc_u32 s15, s15, 0
	s_lshl_b32 s31, s29, 7
	s_add_u32 s14, s14, s31
	s_addc_u32 s15, s15, 0
	s_mov_b32 s22, 4
	s_mov_b32 s20, 0
	s_mov_b64 s[18:19], s[12:13]
	global_load_dword v100, v148, s[18:19]
	s_add_u32 s18, s18, 0x4000
	s_addc_u32 s19, s19, 0
	global_load_dword v101, v148, s[18:19]
	s_add_u32 s18, s18, 0x4000
	s_addc_u32 s19, s19, 0
	global_load_dword v102, v148, s[18:19]
	s_add_u32 s18, s18, 0x4000
	s_addc_u32 s19, s19, 0
	global_load_dword v103, v148, s[18:19]
	s_add_u32 s18, s18, 0x4000
	s_addc_u32 s19, s19, 0
	global_load_dword v104, v148, s[18:19]
	s_add_u32 s18, s18, 0x4000
	s_addc_u32 s19, s19, 0
	global_load_dword v105, v148, s[18:19]
	s_add_u32 s18, s18, 0x4000
	s_addc_u32 s19, s19, 0
	global_load_dword v106, v148, s[18:19]
	s_add_u32 s18, s18, 0x4000
	s_addc_u32 s19, s19, 0
	global_load_dword v107, v148, s[18:19]
	s_add_u32 s18, s18, 0x4000
	s_addc_u32 s19, s19, 0
	global_load_dword v108, v148, s[18:19]
	s_add_u32 s18, s18, 0x4000
	s_addc_u32 s19, s19, 0
	global_load_dword v109, v148, s[18:19]
	s_add_u32 s18, s18, 0x4000
	s_addc_u32 s19, s19, 0
	global_load_dword v110, v148, s[18:19]
	s_add_u32 s18, s18, 0x4000
	s_addc_u32 s19, s19, 0
	global_load_dword v111, v148, s[18:19]
	s_add_u32 s18, s18, 0x4000
	s_addc_u32 s19, s19, 0
	global_load_dword v112, v148, s[18:19]
	s_add_u32 s18, s18, 0x4000
	s_addc_u32 s19, s19, 0
	global_load_dword v113, v148, s[18:19]
	s_add_u32 s18, s18, 0x4000
	s_addc_u32 s19, s19, 0
	global_load_dword v114, v148, s[18:19]
	s_add_u32 s18, s18, 0x4000
	s_addc_u32 s19, s19, 0
	global_load_dword v115, v148, s[18:19]
	s_add_u32 s18, s18, 0x4000
	s_addc_u32 s19, s19, 0
	global_load_dword v116, v148, s[18:19]
	s_add_u32 s18, s18, 0x4000
	s_addc_u32 s19, s19, 0
	global_load_dword v117, v148, s[18:19]
	s_add_u32 s18, s18, 0x4000
	s_addc_u32 s19, s19, 0
	global_load_dword v118, v148, s[18:19]
	s_add_u32 s18, s18, 0x4000
	s_addc_u32 s19, s19, 0
	global_load_dword v119, v148, s[18:19]
	s_add_u32 s18, s18, 0x4000
	s_addc_u32 s19, s19, 0
	global_load_dword v120, v148, s[18:19]
	s_add_u32 s18, s18, 0x4000
	s_addc_u32 s19, s19, 0
	global_load_dword v121, v148, s[18:19]
	s_add_u32 s18, s18, 0x4000
	s_addc_u32 s19, s19, 0
	global_load_dword v122, v148, s[18:19]
	s_add_u32 s18, s18, 0x4000
	s_addc_u32 s19, s19, 0
	global_load_dword v123, v148, s[18:19]
	s_add_u32 s18, s18, 0x4000
	s_addc_u32 s19, s19, 0
	global_load_dword v124, v148, s[18:19]
	s_add_u32 s18, s18, 0x4000
	s_addc_u32 s19, s19, 0
	global_load_dword v125, v148, s[18:19]
	s_add_u32 s18, s18, 0x4000
	s_addc_u32 s19, s19, 0
	global_load_dword v126, v148, s[18:19]
	s_add_u32 s18, s18, 0x4000
	s_addc_u32 s19, s19, 0
	global_load_dword v127, v148, s[18:19]
	s_add_u32 s18, s18, 0x4000
	s_addc_u32 s19, s19, 0
	global_load_dword v128, v148, s[18:19]
	s_add_u32 s18, s18, 0x4000
	s_addc_u32 s19, s19, 0
	global_load_dword v129, v148, s[18:19]
	s_add_u32 s18, s18, 0x4000
	s_addc_u32 s19, s19, 0
	global_load_dword v130, v148, s[18:19]
	s_add_u32 s18, s18, 0x4000
	s_addc_u32 s19, s19, 0
	global_load_dword v131, v148, s[18:19]
	s_add_u32 s12, s12, 0xc00000
	s_addc_u32 s13, s13, 0
